# v61 + norm loop top no longer drains stores (vmcnt(0) removed; loads are covered by vmcnt(4) at row end)
# speedup vs baseline: 1.1246x; 1.0012x over previous
.LBB0_134:
	v_add_u32_e32 v58, s0, v41
	v_add_u32_e32 v8, 0x1000, v58
	v_cmp_gt_i32_e64 s[36:37], s1, v8
	v_cmp_lt_i32_e32 vcc, s35, v8
	s_nop 0
	v_mov_b32_e32 v12, v32
	v_mov_b32_e32 v13, v33
	v_mov_b32_e32 v14, v34
	v_mov_b32_e32 v15, v35
	v_mov_b32_e32 v16, v28
	v_mov_b32_e32 v17, v29
	v_mov_b32_e32 v18, v30
	v_mov_b32_e32 v19, v31
	v_mov_b32_e32 v20, v24
	v_mov_b32_e32 v21, v25
	v_mov_b32_e32 v22, v26
	v_mov_b32_e32 v23, v27
	v_mov_b32_e32 v8, v4
	v_mov_b32_e32 v9, v5
	v_mov_b32_e32 v10, v6
	v_mov_b32_e32 v11, v7
	s_and_saveexec_b64 s[42:43], s[36:37]
	s_cbranch_execz .LBB0_133
	global_load_dwordx4 v[12:15], v[38:39], off offset:-3072
	global_load_dwordx4 v[16:19], v[38:39], off offset:-2048
	global_load_dwordx4 v[20:23], v[38:39], off offset:-1024
	global_load_dwordx4 v[8:11], v[38:39], off
	s_branch .LBB0_133
